# EpiRes (Wo/Down) epilogues: removed the compiler's conservative vmcnt(0) that made the gate loads wait for the next unit's prefetched DMA
# speedup vs baseline: 1.0024x; 1.0024x over previous
;     __device__ __forceinline__ void operator()(const f32x4 (&acc)[2][2][4][2], const pg8::Unit& u, int wr, int wc, int fr, int fq) const {
;         const bool isctx = u.pm >= 128; const int s = isctx ? 4 : (u.pm >> 5);
;         const int col0 = u.pn * 256 + wc * 32 + 8 * fq;
;         const float* gp = gate + s * 6144 + col0;
;         int row0 = (isctx ? u.pm - 128 : u.pm) * 256 + wr * 64 + fr; asm volatile("" : "+v"(row0));
;         f32x4 g[2][2];
; #pragma unroll
;         for (int bj = 0; bj < 2; ++bj) { g[bj][0] = *(const f32x4*)(gp + bj * 128); g[bj][1] = *(const f32x4*)(gp + bj * 128 + 4); }
;         if (u.nt != 0) {
;             float* pp = part + (size_t)(u.k0 / (u.nt * 64)) * MCTX * DM;
; #pragma unroll
;             for (int ai = 0; ai < 2; ++ai)
; #pragma unroll
;                 for (int m = 0; m < 4; ++m) { float* o = pp + (size_t)(row0 + ai * 128 + m * 16) * DM + col0;
; #pragma unroll
;                     for (int bj = 0; bj < 2; ++bj)
; #pragma unroll
;                         for (int n = 0; n < 2; ++n) *(f32x4*)(o + bj * 128 + 4 * n) = g[bj][n] * acc[ai][bj][m][n]; }
.LBB0_539:
	s_cmpk_lt_i32 s0, 0x80
	s_cselect_b64 s[34:35], -1, 0
	s_lshl_b32 s11, s0, 8
	s_lshr_b32 s9, s0, 5
	s_add_i32 s17, s11, 0xffff8000
	s_cmpk_gt_i32 s0, 0x7f
	s_cselect_b64 s[0:1], -1, 0
	s_mulk_i32 s9, 0x1800
	s_and_b64 s[36:37], s[0:1], exec
	s_cselect_b32 s36, 0x6000, s9
	s_cselect_b32 s9, s17, s11
	s_ashr_i32 s37, s36, 31
	v_lshl_or_b32 v170, s10, 8, v186
	s_lshl_b64 s[10:11], s[36:37], 2
	s_add_u32 s10, s61, s10
	s_addc_u32 s11, s62, s11
	v_ashrrev_i32_e32 v171, 31, v170
	v_lshl_add_u64 v[100:101], v[170:171], 2, s[10:11]
	v_add_u32_e32 v172, s9, v184
	global_load_dwordx4 v[104:107], v[100:101], off offset:16
	global_load_dwordx4 v[112:115], v[100:101], off
	global_load_dwordx4 v[92:95], v[100:101], off offset:528
	s_nop 0
	global_load_dwordx4 v[100:103], v[100:101], off offset:512
	s_mov_b64 s[10:11], -1
	s_andn2_b64 vcc, exec, s[30:31]
	v_ashrrev_i32_e32 v173, 31, v172
	s_cbranch_vccnz .LBB0_541
	s_lshl_b32 s9, s82, 6
	v_cvt_f32_u32_e32 v144, s9
	s_sub_i32 s11, 0, s9
	s_ashr_i32 s10, s8, 31
	s_abs_i32 s8, s8
	v_rcp_iflag_f32_e32 v144, v144
	v_lshlrev_b64 v[146:147], 12, v[172:173]
	s_waitcnt vmcnt(0)
	v_pk_mul_f32 v[148:149], v[142:143], v[114:115]
	v_mul_f32_e32 v144, 0x4f7ffffe, v144
	v_cvt_u32_f32_e32 v144, v144
	s_nop 0
	v_readfirstlane_b32 s17, v144
	s_mul_i32 s11, s11, s17
	s_mul_hi_u32 s11, s17, s11
	s_add_i32 s17, s17, s11
	s_mul_hi_u32 s11, s8, s17
	s_mul_i32 s17, s11, s9
	s_sub_i32 s8, s8, s17
	s_add_i32 s17, s11, 1
	s_sub_i32 s19, s8, s9
	s_cmp_ge_u32 s8, s9
	s_cselect_b32 s11, s17, s11
	s_cselect_b32 s8, s19, s8
	s_add_i32 s17, s11, 1
	s_cmp_ge_u32 s8, s9
	s_cselect_b32 s8, s17, s11
	s_xor_b32 s8, s8, s10
	s_sub_i32 s8, s8, s10
	s_ashr_i32 s9, s8, 31
	s_lshl_b64 s[8:9], s[8:9], 22
	v_readlane_b32 s10, v241, 7
	v_readlane_b32 s11, v241, 8
	s_add_u32 s8, s10, s8
	s_addc_u32 s9, s11, s9
	v_lshl_add_u64 v[144:145], v[170:171], 2, s[8:9]
	v_lshl_add_u64 v[144:145], v[144:145], 0, v[146:147]
	v_pk_mul_f32 v[146:147], v[140:141], v[112:113]
	global_store_dwordx4 v[144:145], v[146:149], off
	s_mov_b64 s[8:9], 0x10000
	v_lshl_add_u64 v[150:151], v[144:145], 0, s[8:9]
	v_pk_mul_f32 v[148:149], v[138:139], v[106:107]
	v_pk_mul_f32 v[146:147], v[136:137], v[104:105]
	global_store_dwordx4 v[144:145], v[146:149], off offset:16
	s_mov_b32 s8, 0x10000
	v_add_co_u32_e32 v174, vcc, s8, v144
	v_pk_mul_f32 v[148:149], v[134:135], v[102:103]
	v_pk_mul_f32 v[146:147], v[132:133], v[100:101]
	global_store_dwordx4 v[144:145], v[146:149], off offset:512
	v_addc_co_u32_e32 v175, vcc, 0, v145, vcc
	s_nop 0
	v_pk_mul_f32 v[148:149], v[130:131], v[94:95]
	v_pk_mul_f32 v[146:147], v[128:129], v[92:93]
	global_store_dwordx4 v[144:145], v[146:149], off offset:528
	s_mov_b64 s[8:9], 0x20000
	s_mov_b64 s[10:11], 0
	v_pk_mul_f32 v[148:149], v[126:127], v[114:115]
	v_pk_mul_f32 v[146:147], v[124:125], v[112:113]
	global_store_dwordx4 v[174:175], v[146:149], off
	s_nop 1
	v_pk_mul_f32 v[148:149], v[122:123], v[106:107]
	v_pk_mul_f32 v[146:147], v[120:121], v[104:105]
	global_store_dwordx4 v[150:151], v[146:149], off offset:16
	s_nop 1
	v_pk_mul_f32 v[148:149], v[118:119], v[102:103]
	v_pk_mul_f32 v[146:147], v[116:117], v[100:101]
	global_store_dwordx4 v[150:151], v[146:149], off offset:512
	s_nop 1
	v_pk_mul_f32 v[148:149], v[110:111], v[94:95]
	v_pk_mul_f32 v[146:147], v[108:109], v[92:93]
	global_store_dwordx4 v[150:151], v[146:149], off offset:528
	v_lshl_add_u64 v[150:151], v[144:145], 0, s[8:9]
	s_mov_b32 s8, 0x20000
	v_add_co_u32_e32 v174, vcc, s8, v144
	v_pk_mul_f32 v[148:149], v[98:99], v[114:115]
	v_pk_mul_f32 v[146:147], v[96:97], v[112:113]
	v_addc_co_u32_e32 v175, vcc, 0, v145, vcc
	global_store_dwordx4 v[174:175], v[146:149], off
	s_mov_b64 s[8:9], 0x30000
	s_nop 0
	v_pk_mul_f32 v[148:149], v[90:91], v[106:107]
	v_pk_mul_f32 v[146:147], v[88:89], v[104:105]
	global_store_dwordx4 v[150:151], v[146:149], off offset:16
	s_nop 1
	v_pk_mul_f32 v[148:149], v[86:87], v[102:103]
	v_pk_mul_f32 v[146:147], v[84:85], v[100:101]
	global_store_dwordx4 v[150:151], v[146:149], off offset:512
	s_nop 1
	v_pk_mul_f32 v[148:149], v[82:83], v[94:95]
;     __device__ __forceinline__ void operator()(const f32x4 (&acc)[2][2][4][2], const pg8::Unit& u, int wr, int wc, int fr, int fq) const {
;     ...
;             for (int ai = 0; ai < 2; ++ai)
; #pragma unroll
;                 for (int m = 0; m < 4; ++m) { float* o = pp + (size_t)(row0 + ai * 128 + m * 16) * DM + col0;
; #pragma unroll
;                     for (int bj = 0; bj < 2; ++bj)
; #pragma unroll
;                         for (int n = 0; n < 2; ++n) *(f32x4*)(o + bj * 128 + 4 * n) = g[bj][n] * acc[ai][bj][m][n]; }
;             return;
	v_pk_mul_f32 v[146:147], v[80:81], v[92:93]
	global_store_dwordx4 v[150:151], v[146:149], off offset:528
	v_lshl_add_u64 v[150:151], v[144:145], 0, s[8:9]
	s_mov_b32 s8, 0x30000
	v_add_co_u32_e32 v174, vcc, s8, v144
	v_pk_mul_f32 v[148:149], v[78:79], v[114:115]
	v_pk_mul_f32 v[146:147], v[76:77], v[112:113]
	v_addc_co_u32_e32 v175, vcc, 0, v145, vcc
	global_store_dwordx4 v[174:175], v[146:149], off
	s_mov_b64 s[8:9], 0x80000
	s_nop 0
	v_pk_mul_f32 v[148:149], v[74:75], v[106:107]
	v_pk_mul_f32 v[146:147], v[72:73], v[104:105]
	global_store_dwordx4 v[150:151], v[146:149], off offset:16
	s_nop 1
	v_pk_mul_f32 v[148:149], v[70:71], v[102:103]
	v_pk_mul_f32 v[146:147], v[68:69], v[100:101]
	global_store_dwordx4 v[150:151], v[146:149], off offset:512
	s_nop 1
	v_pk_mul_f32 v[148:149], v[66:67], v[94:95]
	v_pk_mul_f32 v[146:147], v[64:65], v[92:93]
	global_store_dwordx4 v[150:151], v[146:149], off offset:528
	v_lshl_add_u64 v[150:151], v[144:145], 0, s[8:9]
	s_mov_b32 s8, 0x80000
	v_add_co_u32_e32 v174, vcc, s8, v144
	v_pk_mul_f32 v[148:149], v[62:63], v[114:115]
	v_pk_mul_f32 v[146:147], v[60:61], v[112:113]
	v_addc_co_u32_e32 v175, vcc, 0, v145, vcc
	global_store_dwordx4 v[174:175], v[146:149], off
	s_mov_b64 s[8:9], 0x90000
	s_nop 0
	v_pk_mul_f32 v[148:149], v[58:59], v[106:107]
	v_pk_mul_f32 v[146:147], v[56:57], v[104:105]
	global_store_dwordx4 v[150:151], v[146:149], off offset:16
	s_nop 1
	v_pk_mul_f32 v[148:149], v[54:55], v[102:103]
	v_pk_mul_f32 v[146:147], v[52:53], v[100:101]
	global_store_dwordx4 v[150:151], v[146:149], off offset:512
	s_nop 1
	v_pk_mul_f32 v[148:149], v[50:51], v[94:95]
	v_pk_mul_f32 v[146:147], v[48:49], v[92:93]
	global_store_dwordx4 v[150:151], v[146:149], off offset:528
	v_lshl_add_u64 v[150:151], v[144:145], 0, s[8:9]
	s_mov_b32 s8, 0x90000
	v_add_co_u32_e32 v174, vcc, s8, v144
	v_pk_mul_f32 v[148:149], v[46:47], v[114:115]
	v_pk_mul_f32 v[146:147], v[44:45], v[112:113]
	v_addc_co_u32_e32 v175, vcc, 0, v145, vcc
	global_store_dwordx4 v[174:175], v[146:149], off
	s_mov_b64 s[8:9], 0xa0000
	s_nop 0
	v_pk_mul_f32 v[148:149], v[42:43], v[106:107]
	v_pk_mul_f32 v[146:147], v[40:41], v[104:105]
	global_store_dwordx4 v[150:151], v[146:149], off offset:16
	s_nop 1
	v_pk_mul_f32 v[148:149], v[38:39], v[102:103]
	v_pk_mul_f32 v[146:147], v[36:37], v[100:101]
	global_store_dwordx4 v[150:151], v[146:149], off offset:512
	s_nop 1
	v_pk_mul_f32 v[148:149], v[34:35], v[94:95]
	v_pk_mul_f32 v[146:147], v[32:33], v[92:93]
	global_store_dwordx4 v[150:151], v[146:149], off offset:528
	v_lshl_add_u64 v[150:151], v[144:145], 0, s[8:9]
	s_mov_b32 s8, 0xa0000
	v_add_co_u32_e32 v174, vcc, s8, v144
	v_pk_mul_f32 v[148:149], v[30:31], v[114:115]
	v_pk_mul_f32 v[146:147], v[28:29], v[112:113]
	v_addc_co_u32_e32 v175, vcc, 0, v145, vcc
	global_store_dwordx4 v[174:175], v[146:149], off
	s_mov_b64 s[8:9], 0xb0000
	s_nop 0
	v_pk_mul_f32 v[148:149], v[26:27], v[106:107]
	v_pk_mul_f32 v[146:147], v[24:25], v[104:105]
	global_store_dwordx4 v[150:151], v[146:149], off offset:16
	s_nop 1
	v_pk_mul_f32 v[148:149], v[22:23], v[102:103]
	v_pk_mul_f32 v[146:147], v[20:21], v[100:101]
	global_store_dwordx4 v[150:151], v[146:149], off offset:512
	s_nop 1
	v_pk_mul_f32 v[148:149], v[18:19], v[94:95]
	v_pk_mul_f32 v[146:147], v[16:17], v[92:93]
	global_store_dwordx4 v[150:151], v[146:149], off offset:528
	v_lshl_add_u64 v[150:151], v[144:145], 0, s[8:9]
	s_mov_b32 s8, 0xb0000
	v_add_co_u32_e32 v144, vcc, s8, v144
	v_pk_mul_f32 v[148:149], v[14:15], v[114:115]
	v_pk_mul_f32 v[146:147], v[12:13], v[112:113]
	v_addc_co_u32_e32 v145, vcc, 0, v145, vcc
	global_store_dwordx4 v[144:145], v[146:149], off
	v_pk_mul_f32 v[144:145], v[8:9], v[104:105]
	s_nop 0
	v_pk_mul_f32 v[146:147], v[10:11], v[106:107]
	global_store_dwordx4 v[150:151], v[144:147], off offset:16
	s_nop 1
	v_pk_mul_f32 v[146:147], v[6:7], v[102:103]
	v_pk_mul_f32 v[144:145], v[4:5], v[100:101]
	global_store_dwordx4 v[150:151], v[144:147], off offset:512
	s_nop 1
	v_pk_mul_f32 v[146:147], v[2:3], v[94:95]
	v_pk_mul_f32 v[144:145], v[0:1], v[92:93]
	global_store_dwordx4 v[150:151], v[144:147], off offset:528

;     __device__ __forceinline__ void operator()(const f32x4 (&acc)[2][2][4][2], const pg8::Unit& u, int wr, int wc, int fr, int fq) const {
;         const bool isctx = u.pm >= 128; const int s = isctx ? 4 : (u.pm >> 5);
;         const int col0 = u.pn * 256 + wc * 32 + 8 * fq;
;         const float* gp = gate + s * 6144 + col0;
;         int row0 = (isctx ? u.pm - 128 : u.pm) * 256 + wr * 64 + fr; asm volatile("" : "+v"(row0));
;         f32x4 g[2][2];
; #pragma unroll
;         for (int bj = 0; bj < 2; ++bj) { g[bj][0] = *(const f32x4*)(gp + bj * 128); g[bj][1] = *(const f32x4*)(gp + bj * 128 + 4); }
;         if (u.nt != 0) {
;             float* pp = part + (size_t)(u.k0 / (u.nt * 64)) * MCTX * DM;
.LBB0_916:
	s_cmpk_lt_i32 s0, 0x80
	s_cselect_b64 s[24:25], -1, 0
	s_lshl_b32 s11, s0, 8
	s_lshr_b32 s9, s0, 5
	s_add_i32 s17, s11, 0xffff8000
	s_cmpk_gt_i32 s0, 0x7f
	s_cselect_b64 s[0:1], -1, 0
	s_mulk_i32 s9, 0x1800
	s_and_b64 s[48:49], s[0:1], exec
	s_cselect_b32 s48, 0x6000, s9
	s_cselect_b32 s9, s17, s11
	s_ashr_i32 s49, s48, 31
	v_lshl_or_b32 v174, s10, 8, v188
	s_lshl_b64 s[10:11], s[48:49], 2
	s_add_u32 s10, s39, s10
	s_addc_u32 s11, s40, s11
	v_ashrrev_i32_e32 v175, 31, v174
	v_lshl_add_u64 v[88:89], v[174:175], 2, s[10:11]
	v_add_u32_e32 v176, s9, v186
	global_load_dwordx4 v[96:99], v[88:89], off offset:16
	global_load_dwordx4 v[100:103], v[88:89], off
	global_load_dwordx4 v[80:83], v[88:89], off offset:528
	s_nop 0
	global_load_dwordx4 v[88:91], v[88:89], off offset:512
	s_mov_b64 s[10:11], -1
	s_andn2_b64 vcc, exec, s[22:23]
	v_ashrrev_i32_e32 v177, 31, v176
	s_cbranch_vccnz .LBB0_918
	s_lshl_b32 s9, s26, 6
	v_cvt_f32_u32_e32 v144, s9
	s_sub_i32 s11, 0, s9
	s_ashr_i32 s10, s8, 31
	s_abs_i32 s8, s8
	v_rcp_iflag_f32_e32 v144, v144
	v_lshlrev_b64 v[146:147], 12, v[176:177]
	s_waitcnt vmcnt(0)
;     __device__ __forceinline__ void operator()(const f32x4 (&acc)[2][2][4][2], const pg8::Unit& u, int wr, int wc, int fr, int fq) const {
;     ...
;             float* pp = part + (size_t)(u.k0 / (u.nt * 64)) * MCTX * DM;
; #pragma unroll
;             for (int ai = 0; ai < 2; ++ai)
; #pragma unroll
;                 for (int m = 0; m < 4; ++m) { float* o = pp + (size_t)(row0 + ai * 128 + m * 16) * DM + col0;
; #pragma unroll
;                     for (int bj = 0; bj < 2; ++bj)
; #pragma unroll
;                         for (int n = 0; n < 2; ++n) *(f32x4*)(o + bj * 128 + 4 * n) = g[bj][n] * acc[ai][bj][m][n]; }
;             return;
	v_pk_mul_f32 v[148:149], v[142:143], v[102:103]
	v_mul_f32_e32 v144, 0x4f7ffffe, v144
	v_cvt_u32_f32_e32 v144, v144
	s_nop 0
	v_readfirstlane_b32 s17, v144
	s_mul_i32 s11, s11, s17
	s_mul_hi_u32 s11, s17, s11
	s_add_i32 s17, s17, s11
	s_mul_hi_u32 s11, s8, s17
	s_mul_i32 s17, s11, s9
	s_sub_i32 s8, s8, s17
	s_add_i32 s17, s11, 1
	s_sub_i32 s19, s8, s9
	s_cmp_ge_u32 s8, s9
	s_cselect_b32 s11, s17, s11
	s_cselect_b32 s8, s19, s8
	s_add_i32 s17, s11, 1
	s_cmp_ge_u32 s8, s9
	s_cselect_b32 s8, s17, s11
	s_xor_b32 s8, s8, s10
	s_sub_i32 s8, s8, s10
	s_ashr_i32 s9, s8, 31
	s_lshl_b64 s[8:9], s[8:9], 22
	v_readlane_b32 s10, v241, 7
	v_readlane_b32 s11, v241, 8
	s_add_u32 s8, s10, s8
	s_addc_u32 s9, s11, s9
	v_lshl_add_u64 v[144:145], v[174:175], 2, s[8:9]
	v_lshl_add_u64 v[144:145], v[144:145], 0, v[146:147]
	v_pk_mul_f32 v[146:147], v[140:141], v[100:101]
	global_store_dwordx4 v[144:145], v[146:149], off
	s_mov_b64 s[8:9], 0x10000
	v_lshl_add_u64 v[150:151], v[144:145], 0, s[8:9]
	v_pk_mul_f32 v[148:149], v[138:139], v[98:99]
	v_pk_mul_f32 v[146:147], v[136:137], v[96:97]
	global_store_dwordx4 v[144:145], v[146:149], off offset:16
	s_mov_b32 s8, 0x10000
	v_add_co_u32_e32 v178, vcc, s8, v144
	v_pk_mul_f32 v[148:149], v[134:135], v[90:91]
	v_pk_mul_f32 v[146:147], v[132:133], v[88:89]
	global_store_dwordx4 v[144:145], v[146:149], off offset:512
	v_addc_co_u32_e32 v179, vcc, 0, v145, vcc
	s_nop 0
	v_pk_mul_f32 v[148:149], v[130:131], v[82:83]
	v_pk_mul_f32 v[146:147], v[128:129], v[80:81]
	global_store_dwordx4 v[144:145], v[146:149], off offset:528
	s_mov_b64 s[8:9], 0x20000
	s_mov_b64 s[10:11], 0
	v_pk_mul_f32 v[148:149], v[126:127], v[102:103]
	v_pk_mul_f32 v[146:147], v[124:125], v[100:101]
	global_store_dwordx4 v[178:179], v[146:149], off
	s_nop 1
	v_pk_mul_f32 v[148:149], v[122:123], v[98:99]
	v_pk_mul_f32 v[146:147], v[120:121], v[96:97]
	global_store_dwordx4 v[150:151], v[146:149], off offset:16
	s_nop 1
	v_pk_mul_f32 v[148:149], v[118:119], v[90:91]
	v_pk_mul_f32 v[146:147], v[116:117], v[88:89]
	global_store_dwordx4 v[150:151], v[146:149], off offset:512
	s_nop 1
	v_pk_mul_f32 v[148:149], v[114:115], v[82:83]
	v_pk_mul_f32 v[146:147], v[112:113], v[80:81]
	global_store_dwordx4 v[150:151], v[146:149], off offset:528
	v_lshl_add_u64 v[150:151], v[144:145], 0, s[8:9]
	s_mov_b32 s8, 0x20000
	v_add_co_u32_e32 v178, vcc, s8, v144
	v_pk_mul_f32 v[148:149], v[110:111], v[102:103]
	v_pk_mul_f32 v[146:147], v[108:109], v[100:101]
	v_addc_co_u32_e32 v179, vcc, 0, v145, vcc
	global_store_dwordx4 v[178:179], v[146:149], off
	s_mov_b64 s[8:9], 0x30000
	s_nop 0
	v_pk_mul_f32 v[148:149], v[106:107], v[98:99]
	v_pk_mul_f32 v[146:147], v[104:105], v[96:97]
	global_store_dwordx4 v[150:151], v[146:149], off offset:16
	s_nop 1
	v_pk_mul_f32 v[148:149], v[94:95], v[90:91]
	v_pk_mul_f32 v[146:147], v[92:93], v[88:89]
	global_store_dwordx4 v[150:151], v[146:149], off offset:512
	s_nop 1
	v_pk_mul_f32 v[148:149], v[86:87], v[82:83]
	v_pk_mul_f32 v[146:147], v[84:85], v[80:81]
	global_store_dwordx4 v[150:151], v[146:149], off offset:528
	v_lshl_add_u64 v[150:151], v[144:145], 0, s[8:9]
	s_mov_b32 s8, 0x30000
	v_add_co_u32_e32 v178, vcc, s8, v144
	v_pk_mul_f32 v[148:149], v[78:79], v[102:103]
	v_pk_mul_f32 v[146:147], v[76:77], v[100:101]
	v_addc_co_u32_e32 v179, vcc, 0, v145, vcc
	global_store_dwordx4 v[178:179], v[146:149], off
	s_mov_b64 s[8:9], 0x80000
	s_nop 0
	v_pk_mul_f32 v[148:149], v[74:75], v[98:99]
	v_pk_mul_f32 v[146:147], v[72:73], v[96:97]
	global_store_dwordx4 v[150:151], v[146:149], off offset:16
	s_nop 1
	v_pk_mul_f32 v[148:149], v[70:71], v[90:91]
	v_pk_mul_f32 v[146:147], v[68:69], v[88:89]
	global_store_dwordx4 v[150:151], v[146:149], off offset:512
	s_nop 1
	v_pk_mul_f32 v[148:149], v[66:67], v[82:83]
	v_pk_mul_f32 v[146:147], v[64:65], v[80:81]
	global_store_dwordx4 v[150:151], v[146:149], off offset:528
	v_lshl_add_u64 v[150:151], v[144:145], 0, s[8:9]
	s_mov_b32 s8, 0x80000
	v_add_co_u32_e32 v178, vcc, s8, v144
	v_pk_mul_f32 v[148:149], v[62:63], v[102:103]
	v_pk_mul_f32 v[146:147], v[60:61], v[100:101]
	v_addc_co_u32_e32 v179, vcc, 0, v145, vcc
	global_store_dwordx4 v[178:179], v[146:149], off
	s_mov_b64 s[8:9], 0x90000
	s_nop 0
	v_pk_mul_f32 v[148:149], v[58:59], v[98:99]
	v_pk_mul_f32 v[146:147], v[56:57], v[96:97]
	global_store_dwordx4 v[150:151], v[146:149], off offset:16
	s_nop 1
	v_pk_mul_f32 v[148:149], v[54:55], v[90:91]
	v_pk_mul_f32 v[146:147], v[52:53], v[88:89]
	global_store_dwordx4 v[150:151], v[146:149], off offset:512
	s_nop 1
	v_pk_mul_f32 v[148:149], v[50:51], v[82:83]
	v_pk_mul_f32 v[146:147], v[48:49], v[80:81]
	global_store_dwordx4 v[150:151], v[146:149], off offset:528
	v_lshl_add_u64 v[150:151], v[144:145], 0, s[8:9]
	s_mov_b32 s8, 0x90000
	v_add_co_u32_e32 v178, vcc, s8, v144
	v_pk_mul_f32 v[148:149], v[46:47], v[102:103]
	v_pk_mul_f32 v[146:147], v[44:45], v[100:101]
	v_addc_co_u32_e32 v179, vcc, 0, v145, vcc
	global_store_dwordx4 v[178:179], v[146:149], off
	s_mov_b64 s[8:9], 0xa0000
	s_nop 0
	v_pk_mul_f32 v[148:149], v[42:43], v[98:99]
	v_pk_mul_f32 v[146:147], v[40:41], v[96:97]
	global_store_dwordx4 v[150:151], v[146:149], off offset:16
	s_nop 1
	v_pk_mul_f32 v[148:149], v[38:39], v[90:91]
	v_pk_mul_f32 v[146:147], v[36:37], v[88:89]
	global_store_dwordx4 v[150:151], v[146:149], off offset:512
	s_nop 1
	v_pk_mul_f32 v[148:149], v[34:35], v[82:83]
	v_pk_mul_f32 v[146:147], v[32:33], v[80:81]
	global_store_dwordx4 v[150:151], v[146:149], off offset:528
	v_lshl_add_u64 v[150:151], v[144:145], 0, s[8:9]
	s_mov_b32 s8, 0xa0000
	v_add_co_u32_e32 v178, vcc, s8, v144
	v_pk_mul_f32 v[148:149], v[30:31], v[102:103]
	v_pk_mul_f32 v[146:147], v[28:29], v[100:101]
	v_addc_co_u32_e32 v179, vcc, 0, v145, vcc
	global_store_dwordx4 v[178:179], v[146:149], off
	s_mov_b64 s[8:9], 0xb0000
	s_nop 0
	v_pk_mul_f32 v[148:149], v[26:27], v[98:99]
	v_pk_mul_f32 v[146:147], v[24:25], v[96:97]
	global_store_dwordx4 v[150:151], v[146:149], off offset:16
	s_nop 1
	v_pk_mul_f32 v[148:149], v[22:23], v[90:91]
	v_pk_mul_f32 v[146:147], v[20:21], v[88:89]
	global_store_dwordx4 v[150:151], v[146:149], off offset:512
	s_nop 1
	v_pk_mul_f32 v[148:149], v[18:19], v[82:83]
	v_pk_mul_f32 v[146:147], v[16:17], v[80:81]
	global_store_dwordx4 v[150:151], v[146:149], off offset:528
	v_lshl_add_u64 v[150:151], v[144:145], 0, s[8:9]
	s_mov_b32 s8, 0xb0000
	v_add_co_u32_e32 v144, vcc, s8, v144
	v_pk_mul_f32 v[148:149], v[14:15], v[102:103]
	v_pk_mul_f32 v[146:147], v[12:13], v[100:101]
	v_addc_co_u32_e32 v145, vcc, 0, v145, vcc
	global_store_dwordx4 v[144:145], v[146:149], off
	v_pk_mul_f32 v[144:145], v[8:9], v[96:97]
	s_nop 0
	v_pk_mul_f32 v[146:147], v[10:11], v[98:99]
	global_store_dwordx4 v[150:151], v[144:147], off offset:16
	s_nop 1
	v_pk_mul_f32 v[146:147], v[6:7], v[90:91]
	v_pk_mul_f32 v[144:145], v[4:5], v[88:89]
	global_store_dwordx4 v[150:151], v[144:147], off offset:512
	s_nop 1
	v_pk_mul_f32 v[146:147], v[2:3], v[82:83]
	v_pk_mul_f32 v[144:145], v[0:1], v[80:81]
	global_store_dwordx4 v[150:151], v[144:147], off offset:528
